# v10 + non-leader workgroups poll the cross-XCD release word directly at the four global barriers (one hop fewer)
# speedup vs baseline: 1.0023x; 1.0019x over previous
; __device__ __forceinline__ unsigned xb_ld(unsigned* p)              { return __hip_atomic_load(p, __ATOMIC_RELAXED, __HIP_MEMORY_SCOPE_AGENT); }
; __device__ __forceinline__ unsigned xb_add(unsigned* p, unsigned v) { return __hip_atomic_fetch_add(p, v, __ATOMIC_RELAXED, __HIP_MEMORY_SCOPE_AGENT); }
; #define XB_SPIN(cond, bar) do { unsigned _sp = 0; while (cond) { __builtin_amdgcn_s_sleep(1); \
;     if ((++_sp & 255u) == 0u) { if (xb_ld(&(bar)[XB_TMO])) break; if (_sp > XB_SPIN_CAP) { atomicAdd(&(bar)[XB_TMO], 1u); break; } } } } while (0)
; __device__ __forceinline__ void xcd_barrier(const XcdBarrier& b) {
;     ...
;         unsigned nloc = b.st[0], nx = b.st[1];
;         if (nloc == 0u) { xcd_barrier_complete(bar, b.x, nloc, nx); b.st[0] = nloc; b.st[1] = nx; }
;         const unsigned old = xb_add(&bar[XB_XSUB(b.x)], 1u);
;         const unsigned gen = old / nloc;
;         if (old + 1u == (gen + 1u) * nloc) {
;             __builtin_amdgcn_fence(__ATOMIC_RELEASE, "agent");
;             asm volatile("s_waitcnt vmcnt(0)" ::: "memory");
;             const unsigned og = xb_add(&bar[XB_TOP], 1u);
;             const unsigned tg = og / nx;
;             if (og + 1u == (tg + 1u) * nx) xb_add(&bar[XB_TOPGEN], 1u);
;             else XB_SPIN(xb_ld(&bar[XB_TOPGEN]) == tg, bar);
;             __builtin_amdgcn_fence(__ATOMIC_ACQUIRE, "agent");
;             xb_add(&bar[XB_XGEN(b.x)], 1u);
;             asm volatile("s_waitcnt vmcnt(0)" ::: "memory");
;         } else {
;             XB_SPIN(xb_ld(&bar[XB_XGEN(b.x)]) == gen, bar);
;             __builtin_amdgcn_fence(__ATOMIC_ACQUIRE, "agent");
;             asm volatile("s_waitcnt vmcnt(0)" ::: "memory");
.LBB0_94:
	s_or_b64 exec, exec, s[12:13]
	v_cvt_f32_u32_e32 v4, v2
	s_waitcnt vmcnt(0)
	v_readfirstlane_b32 s4, v3
	v_sub_u32_e32 v3, 0, v2
	v_rcp_iflag_f32_e32 v4, v4
	v_add_u32_e32 v5, s4, v1
	v_mul_f32_e32 v4, 0x4f7ffffe, v4
	v_cvt_u32_f32_e32 v4, v4
	v_mul_lo_u32 v1, v3, v4
	v_mul_hi_u32 v1, v4, v1
	v_add_u32_e32 v1, v4, v1
	v_mul_hi_u32 v1, v5, v1
	v_mul_lo_u32 v3, v1, v2
	v_sub_u32_e32 v3, v5, v3
	v_add_u32_e32 v4, 1, v1
	v_cmp_ge_u32_e32 vcc, v3, v2
	s_nop 1
	v_cndmask_b32_e32 v1, v1, v4, vcc
	v_sub_u32_e32 v4, v3, v2
	v_cndmask_b32_e32 v3, v3, v4, vcc
	v_add_u32_e32 v4, 1, v1
	v_cmp_ge_u32_e32 vcc, v3, v2
	v_add_u32_e32 v3, 1, v5
	s_nop 0
	v_cndmask_b32_e32 v1, v1, v4, vcc
	v_mul_lo_u32 v4, v2, v1
	v_add_u32_e32 v2, v4, v2
	v_cmp_ne_u32_e32 vcc, v3, v2
	s_and_saveexec_b64 s[4:5], vcc
	s_xor_b64 s[10:11], exec, s[4:5]
	s_cbranch_execz .LBB0_108
	s_waitcnt lgkmcnt(0)
	v_mov_b32_e32 v0, 0x13000
	global_load_dword v0, v0, s[28:29] offset:1280 sc1
	s_add_u32 s16, s28, 0x13500
	s_addc_u32 s17, s29, 0
	s_waitcnt vmcnt(0)
	v_cmp_eq_u32_e32 vcc, v0, v1
	s_and_saveexec_b64 s[12:13], vcc
	s_cbranch_execz .LBB0_107
	s_add_u32 s14, s28, 0x10200
	s_addc_u32 s15, s29, 0
	s_mov_b32 s4, 1
	s_mov_b64 s[18:19], 0
	v_mov_b32_e32 v0, 0
	s_branch .LBB0_98

; __device__ __forceinline__ unsigned xb_ld(unsigned* p)              { return __hip_atomic_load(p, __ATOMIC_RELAXED, __HIP_MEMORY_SCOPE_AGENT); }
; __device__ __forceinline__ unsigned xb_add(unsigned* p, unsigned v) { return __hip_atomic_fetch_add(p, v, __ATOMIC_RELAXED, __HIP_MEMORY_SCOPE_AGENT); }
; #define XB_SPIN(cond, bar) do { unsigned _sp = 0; while (cond) { __builtin_amdgcn_s_sleep(1); \
;     if ((++_sp & 255u) == 0u) { if (xb_ld(&(bar)[XB_TMO])) break; if (_sp > XB_SPIN_CAP) { atomicAdd(&(bar)[XB_TMO], 1u); break; } } } } while (0)
; __device__ __forceinline__ void xcd_barrier(const XcdBarrier& b) {
;     ...
;         unsigned nloc = b.st[0], nx = b.st[1];
;         if (nloc == 0u) { xcd_barrier_complete(bar, b.x, nloc, nx); b.st[0] = nloc; b.st[1] = nx; }
;         const unsigned old = xb_add(&bar[XB_XSUB(b.x)], 1u);
;         const unsigned gen = old / nloc;
;         if (old + 1u == (gen + 1u) * nloc) {
;             __builtin_amdgcn_fence(__ATOMIC_RELEASE, "agent");
;             asm volatile("s_waitcnt vmcnt(0)" ::: "memory");
;             const unsigned og = xb_add(&bar[XB_TOP], 1u);
;             const unsigned tg = og / nx;
;             if (og + 1u == (tg + 1u) * nx) xb_add(&bar[XB_TOPGEN], 1u);
;             else XB_SPIN(xb_ld(&bar[XB_TOPGEN]) == tg, bar);
;             __builtin_amdgcn_fence(__ATOMIC_ACQUIRE, "agent");
;             xb_add(&bar[XB_XGEN(b.x)], 1u);
;             asm volatile("s_waitcnt vmcnt(0)" ::: "memory");
;         } else {
;             XB_SPIN(xb_ld(&bar[XB_XGEN(b.x)]) == gen, bar);
;             __builtin_amdgcn_fence(__ATOMIC_ACQUIRE, "agent");
;             asm volatile("s_waitcnt vmcnt(0)" ::: "memory");
.LBB0_537:
	s_or_b64 exec, exec, s[12:13]
	v_cvt_f32_u32_e32 v4, v2
	s_waitcnt vmcnt(0)
	v_readfirstlane_b32 s3, v3
	v_sub_u32_e32 v3, 0, v2
	v_rcp_iflag_f32_e32 v4, v4
	v_add_u32_e32 v5, s3, v1
	v_mul_f32_e32 v4, 0x4f7ffffe, v4
	v_cvt_u32_f32_e32 v4, v4
	v_mul_lo_u32 v1, v3, v4
	v_mul_hi_u32 v1, v4, v1
	v_add_u32_e32 v1, v4, v1
	v_mul_hi_u32 v1, v5, v1
	v_mul_lo_u32 v3, v1, v2
	v_sub_u32_e32 v3, v5, v3
	v_add_u32_e32 v4, 1, v1
	v_cmp_ge_u32_e32 vcc, v3, v2
	s_nop 1
	v_cndmask_b32_e32 v1, v1, v4, vcc
	v_sub_u32_e32 v4, v3, v2
	v_cndmask_b32_e32 v3, v3, v4, vcc
	v_add_u32_e32 v4, 1, v1
	v_cmp_ge_u32_e32 vcc, v3, v2
	v_add_u32_e32 v3, 1, v5
	s_nop 0
	v_cndmask_b32_e32 v1, v1, v4, vcc
	v_mul_lo_u32 v4, v2, v1
	v_add_u32_e32 v2, v4, v2
	v_cmp_ne_u32_e32 vcc, v3, v2
	s_and_saveexec_b64 s[4:5], vcc
	s_xor_b64 s[10:11], exec, s[4:5]
	s_cbranch_execz .LBB0_551
	s_waitcnt lgkmcnt(0)
	v_mov_b32_e32 v0, 0x13000
	global_load_dword v0, v0, s[28:29] offset:1280 sc1
	s_add_u32 s16, s28, 0x13500
	s_addc_u32 s17, s29, 0
	s_waitcnt vmcnt(0)
	v_cmp_eq_u32_e32 vcc, v0, v1
	s_and_saveexec_b64 s[12:13], vcc
	s_cbranch_execz .LBB0_550
	s_add_u32 s14, s28, 0x10200
	s_addc_u32 s15, s29, 0
	s_mov_b32 s3, 1
	s_mov_b64 s[18:19], 0
	v_mov_b32_e32 v0, 0
	s_branch .LBB0_541

; __device__ __forceinline__ unsigned xb_ld(unsigned* p)              { return __hip_atomic_load(p, __ATOMIC_RELAXED, __HIP_MEMORY_SCOPE_AGENT); }
; __device__ __forceinline__ unsigned xb_add(unsigned* p, unsigned v) { return __hip_atomic_fetch_add(p, v, __ATOMIC_RELAXED, __HIP_MEMORY_SCOPE_AGENT); }
; #define XB_SPIN(cond, bar) do { unsigned _sp = 0; while (cond) { __builtin_amdgcn_s_sleep(1); \
;     if ((++_sp & 255u) == 0u) { if (xb_ld(&(bar)[XB_TMO])) break; if (_sp > XB_SPIN_CAP) { atomicAdd(&(bar)[XB_TMO], 1u); break; } } } } while (0)
; __device__ __forceinline__ void xcd_barrier(const XcdBarrier& b) {
;     ...
;         unsigned nloc = b.st[0], nx = b.st[1];
;         if (nloc == 0u) { xcd_barrier_complete(bar, b.x, nloc, nx); b.st[0] = nloc; b.st[1] = nx; }
;         const unsigned old = xb_add(&bar[XB_XSUB(b.x)], 1u);
;         const unsigned gen = old / nloc;
;         if (old + 1u == (gen + 1u) * nloc) {
;             __builtin_amdgcn_fence(__ATOMIC_RELEASE, "agent");
;             asm volatile("s_waitcnt vmcnt(0)" ::: "memory");
;             const unsigned og = xb_add(&bar[XB_TOP], 1u);
;             const unsigned tg = og / nx;
;             if (og + 1u == (tg + 1u) * nx) xb_add(&bar[XB_TOPGEN], 1u);
;             else XB_SPIN(xb_ld(&bar[XB_TOPGEN]) == tg, bar);
;             __builtin_amdgcn_fence(__ATOMIC_ACQUIRE, "agent");
;             xb_add(&bar[XB_XGEN(b.x)], 1u);
;             asm volatile("s_waitcnt vmcnt(0)" ::: "memory");
;         } else {
;             XB_SPIN(xb_ld(&bar[XB_XGEN(b.x)]) == gen, bar);
;             __builtin_amdgcn_fence(__ATOMIC_ACQUIRE, "agent");
;             asm volatile("s_waitcnt vmcnt(0)" ::: "memory");
.LBB0_731:
	s_or_b64 exec, exec, s[14:15]
	v_cvt_f32_u32_e32 v4, v2
	s_waitcnt vmcnt(0)
	v_readfirstlane_b32 s4, v3
	v_sub_u32_e32 v3, 0, v2
	v_rcp_iflag_f32_e32 v4, v4
	v_add_u32_e32 v5, s4, v1
	v_mul_f32_e32 v4, 0x4f7ffffe, v4
	v_cvt_u32_f32_e32 v4, v4
	v_mul_lo_u32 v1, v3, v4
	v_mul_hi_u32 v1, v4, v1
	v_add_u32_e32 v1, v4, v1
	v_mul_hi_u32 v1, v5, v1
	v_mul_lo_u32 v3, v1, v2
	v_sub_u32_e32 v3, v5, v3
	v_add_u32_e32 v4, 1, v1
	v_cmp_ge_u32_e32 vcc, v3, v2
	s_nop 1
	v_cndmask_b32_e32 v1, v1, v4, vcc
	v_sub_u32_e32 v4, v3, v2
	v_cndmask_b32_e32 v3, v3, v4, vcc
	v_add_u32_e32 v4, 1, v1
	v_cmp_ge_u32_e32 vcc, v3, v2
	v_add_u32_e32 v3, 1, v5
	s_nop 0
	v_cndmask_b32_e32 v1, v1, v4, vcc
	v_mul_lo_u32 v4, v2, v1
	v_add_u32_e32 v2, v4, v2
	v_cmp_ne_u32_e32 vcc, v3, v2
	s_and_saveexec_b64 s[4:5], vcc
	s_xor_b64 s[12:13], exec, s[4:5]
	s_cbranch_execz .LBB0_745
	s_waitcnt lgkmcnt(0)
	v_mov_b32_e32 v0, 0x13000
	global_load_dword v0, v0, s[28:29] offset:1280 sc1
	s_add_u32 s18, s28, 0x13500
	s_addc_u32 s19, s29, 0
	s_waitcnt vmcnt(0)
	v_cmp_eq_u32_e32 vcc, v0, v1
	s_and_saveexec_b64 s[14:15], vcc
	s_cbranch_execz .LBB0_744
	s_add_u32 s16, s28, 0x10200
	s_addc_u32 s17, s29, 0
	s_mov_b32 s4, 1
	s_mov_b64 s[20:21], 0
	v_mov_b32_e32 v0, 0
	s_branch .LBB0_735
